# fox queue index fetched one unit ahead; gate-up tile order division by constant group size; fox log-forget values staged to LDS by all waves; band rel-bias load issued at iteration top
# baseline (speedup 1.0000x reference)
; #define LAS __attribute__((address_space(3)))
; template <int FOX> __device__ __forceinline__ void sample_unit(int s, int h, LAS unsigned char* lds, const KA& A) {
;     ...
;         for (int i = 0; i < 16; ++i) { float a = 0.f;
; #pragma unroll
;             for (int q = 0; q < 16; ++q) { const f32x4 qv = *(const LAS f32x4*)(Qs + i * 64 + 4 * q); a += (qv.x * kr[q].x + qv.y * kr[q].y) + (qv.z * kr[q].z + qv.w * kr[q].w); }
;             float bias; bool valid = true;
;             if (FOX) { bias = L2E * (cum[NC + i] - cj); valid = (j <= NC + i); }
;             else { int dist = 512 + i - j; dist = dist > 256 ? 256 : dist; dist = dist < -256 ? -256 : dist; bias = L2E * relb[(dist + 256) * 16]; }
;             S[i * SP + j] = valid ? a + bias : -INFINITY; }
.LBB0_173:
	s_add_i32 s54, s53, 0
	v_mov_b32_e32 v71, s54
	ds_read_b128 v[72:75], v71
	ds_read_b128 v[76:79], v71 offset:16
	ds_read_b128 v[80:83], v71 offset:32
	ds_read_b128 v[84:87], v71 offset:48
	s_movk_i32 s54, 0xff00
	v_med3_i32 v90, v70, s54, v218
	v_lshlrev_b32_e32 v90, 4, v90
	v_ashrrev_i32_e32 v91, 31, v90
	v_lshl_add_u64 v[90:91], v[90:91], 2, s[44:45]
	v_add_co_u32_e32 v90, vcc, 0x4000, v90
	s_nop 1
	v_addc_co_u32_e32 v91, vcc, 0, v91, vcc
	global_load_dword v92, v[90:91], off
	s_waitcnt vmcnt(12) lgkmcnt(3)
	v_pk_mul_f32 v[74:75], v[18:19], v[74:75]
	v_pk_mul_f32 v[72:73], v[16:17], v[72:73]
	s_waitcnt lgkmcnt(2)
	v_pk_mul_f32 v[76:77], v[12:13], v[76:77]
	v_pk_mov_b32 v[88:89], v[72:73], v[74:75] op_sel:[1,0]
	v_mov_b32_e32 v73, v75
	v_pk_mul_f32 v[74:75], v[14:15], v[78:79]
	v_pk_add_f32 v[72:73], v[88:89], v[72:73]
	v_pk_mov_b32 v[78:79], v[76:77], v[74:75] op_sel:[1,0]
	v_mov_b32_e32 v77, v75
	v_pk_add_f32 v[74:75], v[78:79], v[76:77]
	v_add_f32_e32 v72, v72, v73
	s_waitcnt lgkmcnt(0)
	v_mul_f32_e32 v76, v5, v85
	v_pk_add_f32 v[74:75], v[74:75], v[74:75] op_sel:[0,1] op_sel_hi:[1,0]
	v_add_f32_e32 v72, 0, v72
	v_mul_f32_e32 v73, v4, v84
	v_mov_b32_e32 v75, v76
	v_pk_add_f32 v[72:73], v[72:73], v[74:75]
	v_mul_f32_e32 v74, v9, v81
	v_mul_f32_e32 v77, v6, v86
	v_pk_fma_f32 v[74:75], v[8:9], v[80:81], v[74:75] op_sel_hi:[1,1,0]
	v_mul_f32_e32 v76, v11, v83
	v_mul_f32_e32 v78, v7, v87
	v_mov_b32_e32 v75, v77
	v_pk_fma_f32 v[76:77], v[10:11], v[82:83], v[76:77] op_sel_hi:[1,1,0]
	s_addk_i32 s53, 0x100
	v_mov_b32_e32 v77, v78
	v_pk_add_f32 v[74:75], v[74:75], v[76:77]
	s_cmpk_lg_i32 s53, 0x1000
	v_pk_add_f32 v[80:81], v[72:73], v[74:75]
	ds_read_b128 v[72:75], v71 offset:64
	s_waitcnt vmcnt(8) lgkmcnt(0)
	v_pk_mul_f32 v[74:75], v[34:35], v[74:75]
	v_pk_mul_f32 v[72:73], v[32:33], v[72:73]
	s_nop 0
	v_pk_mov_b32 v[76:77], v[72:73], v[74:75] op_sel:[1,0]
	v_mov_b32_e32 v73, v75
	v_pk_add_f32 v[82:83], v[76:77], v[72:73]
	ds_read_b128 v[72:75], v71 offset:80
	ds_read_b128 v[76:79], v71 offset:96
	s_waitcnt lgkmcnt(0)
	v_mul_f32_e32 v84, v20, v76
	v_mul_f32_e32 v85, v21, v77
	v_mul_f32_e32 v86, v22, v78
	v_mul_f32_e32 v87, v23, v79
	v_pk_add_f32 v[76:77], v[80:81], v[80:81] op_sel:[0,1] op_sel_hi:[1,0]
	v_pk_add_f32 v[78:79], v[82:83], v[82:83] op_sel:[0,1] op_sel_hi:[1,0]
	v_mov_b32_e32 v77, v84
	v_mov_b32_e32 v79, v85
	v_pk_add_f32 v[76:77], v[76:77], v[78:79]
	v_mul_f32_e32 v78, v29, v73
	v_pk_fma_f32 v[72:73], v[28:29], v[72:73], v[78:79] op_sel_hi:[1,1,0]
	v_mul_f32_e32 v78, v31, v75
	v_pk_fma_f32 v[74:75], v[30:31], v[74:75], v[78:79] op_sel_hi:[1,1,0]
	v_mov_b32_e32 v73, v86
	v_mov_b32_e32 v75, v87
	v_pk_add_f32 v[72:73], v[72:73], v[74:75]
	s_nop 0
	v_pk_add_f32 v[80:81], v[76:77], v[72:73]
	ds_read_b128 v[72:75], v71 offset:112
	s_waitcnt lgkmcnt(0)
	v_pk_mul_f32 v[74:75], v[26:27], v[74:75]
	v_pk_mul_f32 v[72:73], v[24:25], v[72:73]
	s_nop 0
	v_pk_mov_b32 v[76:77], v[72:73], v[74:75] op_sel:[1,0]
	v_mov_b32_e32 v73, v75
	v_pk_add_f32 v[82:83], v[76:77], v[72:73]
	ds_read_b128 v[72:75], v71 offset:128
	ds_read_b128 v[76:79], v71 offset:144
	s_waitcnt vmcnt(5) lgkmcnt(0)
	v_mul_f32_e32 v84, v44, v76
	v_mul_f32_e32 v85, v45, v77
	v_mul_f32_e32 v86, v46, v78
	v_mul_f32_e32 v87, v47, v79
	v_pk_add_f32 v[76:77], v[80:81], v[80:81] op_sel:[0,1] op_sel_hi:[1,0]
	v_pk_add_f32 v[78:79], v[82:83], v[82:83] op_sel:[0,1] op_sel_hi:[1,0]
	v_mov_b32_e32 v77, v84
	v_mov_b32_e32 v79, v85
	v_pk_add_f32 v[76:77], v[76:77], v[78:79]
	s_waitcnt vmcnt(4)
	v_mul_f32_e32 v78, v49, v73
	v_pk_fma_f32 v[72:73], v[48:49], v[72:73], v[78:79] op_sel_hi:[1,1,0]
	v_mul_f32_e32 v78, v51, v75
	v_pk_fma_f32 v[74:75], v[50:51], v[74:75], v[78:79] op_sel_hi:[1,1,0]
	v_mov_b32_e32 v73, v86
	v_mov_b32_e32 v75, v87
	v_pk_add_f32 v[72:73], v[72:73], v[74:75]
	s_nop 0
	v_pk_add_f32 v[80:81], v[76:77], v[72:73]
	ds_read_b128 v[72:75], v71 offset:160
	s_waitcnt lgkmcnt(0)
	v_pk_mul_f32 v[74:75], v[42:43], v[74:75]
	v_pk_mul_f32 v[72:73], v[40:41], v[72:73]
	s_nop 0
	v_pk_mov_b32 v[76:77], v[72:73], v[74:75] op_sel:[1,0]
	v_mov_b32_e32 v73, v75
	v_pk_add_f32 v[82:83], v[76:77], v[72:73]
	ds_read_b128 v[72:75], v71 offset:176
	ds_read_b128 v[76:79], v71 offset:192
	s_waitcnt vmcnt(1) lgkmcnt(0)
	v_mul_f32_e32 v84, v60, v76
	v_mul_f32_e32 v85, v61, v77
	v_mul_f32_e32 v86, v62, v78
	v_mul_f32_e32 v87, v63, v79
	v_pk_add_f32 v[76:77], v[80:81], v[80:81] op_sel:[0,1] op_sel_hi:[1,0]
	v_pk_add_f32 v[78:79], v[82:83], v[82:83] op_sel:[0,1] op_sel_hi:[1,0]
	v_mov_b32_e32 v77, v84
	v_mov_b32_e32 v79, v85
	v_pk_add_f32 v[76:77], v[76:77], v[78:79]
	v_mul_f32_e32 v78, v37, v73
	v_pk_fma_f32 v[72:73], v[36:37], v[72:73], v[78:79] op_sel_hi:[1,1,0]
	v_mul_f32_e32 v78, v39, v75
	v_pk_fma_f32 v[74:75], v[38:39], v[74:75], v[78:79] op_sel_hi:[1,1,0]
	v_mov_b32_e32 v73, v86
	v_mov_b32_e32 v75, v87
	v_pk_add_f32 v[72:73], v[72:73], v[74:75]
	s_nop 0
	v_pk_add_f32 v[80:81], v[76:77], v[72:73]
	ds_read_b128 v[72:75], v71 offset:208
	s_waitcnt vmcnt(0) lgkmcnt(0)
	v_pk_mul_f32 v[74:75], v[66:67], v[74:75]
	v_pk_mul_f32 v[72:73], v[64:65], v[72:73]
	s_nop 0
	v_pk_mov_b32 v[76:77], v[72:73], v[74:75] op_sel:[1,0]
	v_mov_b32_e32 v73, v75
	v_pk_add_f32 v[82:83], v[76:77], v[72:73]
	ds_read_b128 v[72:75], v71 offset:224
	ds_read_b128 v[76:79], v71 offset:240
	s_waitcnt lgkmcnt(0)
	v_mul_f32_e32 v71, v52, v76
	v_mul_f32_e32 v84, v53, v77
	v_mul_f32_e32 v85, v54, v78
	v_mul_f32_e32 v86, v55, v79
	v_pk_add_f32 v[76:77], v[80:81], v[80:81] op_sel:[0,1] op_sel_hi:[1,0]
	v_pk_add_f32 v[78:79], v[82:83], v[82:83] op_sel:[0,1] op_sel_hi:[1,0]
	v_mov_b32_e32 v77, v71
	v_mov_b32_e32 v79, v84
	v_pk_add_f32 v[76:77], v[76:77], v[78:79]
	v_mul_f32_e32 v78, v57, v73
	v_pk_fma_f32 v[72:73], v[56:57], v[72:73], v[78:79] op_sel_hi:[1,1,0]
	v_mul_f32_e32 v78, v59, v75
	v_pk_fma_f32 v[74:75], v[58:59], v[74:75], v[78:79] op_sel_hi:[1,1,0]
	v_mov_b32_e32 v73, v85
	v_mov_b32_e32 v75, v86
	v_pk_add_f32 v[72:73], v[72:73], v[74:75]
	s_nop 0
	v_pk_add_f32 v[72:73], v[76:77], v[72:73]
	s_nop 0
	v_add_f32_e32 v71, v72, v73
	v_add_u32_e32 v70, 1, v70
	s_waitcnt vmcnt(0)
	v_fmac_f32_e32 v71, 0x3fb8aa3b, v92
	v_add_u32_e32 v72, 0, v69
	v_add_u32_e32 v69, 0x1080, v69
	ds_write_b32 v72, v71
	s_cbranch_scc1 .LBB0_173
	v_add_u32_e32 v4, 0x200, v68
	v_cmp_lt_i32_e32 vcc, 15, v68
	v_add_u32_e32 v1, 0xfffffe00, v1
	v_add_u32_e32 v2, 0x800, v2
	s_or_b64 s[40:41], vcc, s[40:41]
	v_mov_b32_e32 v68, v4
	s_andn2_b64 exec, exec, s[40:41]
	s_cbranch_execnz .LBB0_172

; #define LAS __attribute__((address_space(3)))
; __global__ void __launch_bounds__(NWAVES * 64, 2) mk_fwd(Args args) {
;     ...
;                     volatile LAS unsigned* qslot = (volatile LAS unsigned*)(lds3 + RING_OFF + attn_body::ATTN_LDS_BYTES);
; #pragma unroll 1
;                     for (;;) { if (tid == 0) *qslot = __hip_atomic_fetch_add((unsigned*)(ws + WS_CTL) + CW_QUEUE, 1u, __ATOMIC_RELAXED, __HIP_MEMORY_SCOPE_AGENT);
;                         __syncthreads(); const unsigned idx = *qslot; __syncthreads();
;                         if (idx >= 2048u + 256u) break;
.LBB0_193:
	s_andn2_b64 vcc, exec, s[4:5]
	s_cbranch_vccnz .LBB0_348
	s_add_u32 s90, s78, 0x1e3c00
	s_addc_u32 s91, s79, 0
	s_add_u32 s4, s78, 0x10000
	s_addc_u32 s5, s79, 0
	s_add_u32 s88, s76, 0x19500000
	v_writelane_b32 v255, s4, 52
	s_addc_u32 s2, s77, 0
	v_cmp_eq_u32_e64 s[40:41], 0, v228
	v_writelane_b32 v255, s5, 53
	s_add_u32 s4, s76, 0x19600000
	v_writelane_b32 v255, s2, 54
	s_addc_u32 s5, s77, 0
	v_writelane_b32 v255, s4, 55
	s_add_u32 s2, s76, 0x19700000
	s_nop 0
	v_writelane_b32 v255, s5, 56
	v_writelane_b32 v255, s2, 57
	s_addc_u32 s2, s77, 0
	s_add_u32 s8, s78, 0x1b900000
	s_addc_u32 s9, s79, 0
	v_writelane_b32 v255, s2, 58
	s_add_u32 s2, s78, 0x200000
	v_writelane_b32 v255, s2, 59
	s_addc_u32 s2, s79, 0
	v_writelane_b32 v255, s2, 60
	v_readlane_b32 s6, v255, 52
	v_readlane_b32 s7, v255, 53
	s_and_saveexec_b64 s[42:43], s[40:41]
	s_cbranch_execz .Lfq_first
	s_nop 3
	global_atomic_add v248, v3, v216, s[6:7] sc0
.Lfq_first:
	s_mov_b64 exec, s[42:43]
	s_branch .LBB0_198

; template <int FOX> __device__ __forceinline__ void sample_unit(int s, int h, LAS unsigned char* lds, const KA& A) {
;     ...
;     { const int e = tid * 2, i = e >> 6, d = e & 63; const unsigned w = *(const unsigned*)(QO + (size_t)(MP + s * 16 + i) * 1024 + h * 64 + d);
;       Qs[i * 64 + d] = bf2f((unsigned short)(w & 0xffffu)); Qs[i * 64 + d + 1] = bf2f((unsigned short)(w >> 16)); }
;     if (FOX && wave == 0) { const float* clf = A.in[6]; const float* nlf = A.out + O_FLS; float carry = 0.f;
;         for (int c = 0; c < 17; ++c) { const int j = c * 64 + lane;
;             float v = (j < 1024) ? clf[(size_t)(s * 1024 + j) * 16 + h] : ((j < 1040) ? nlf[(size_t)(s * 16 + j - 1024) * 16 + h] : 0.f);
; #pragma unroll
;             for (int d = 1; d < 64; d <<= 1) { const float t = __shfl_up(v, d); if (lane >= d) v += t; }
;             v += carry; if (j < 1040) cum[j] = v; carry = __shfl(v, 63); } }
; __global__ void __launch_bounds__(NWAVES * 64, 2) mk_fwd(Args args) {
;     ...
;                     for (;;) { if (tid == 0) *qslot = __hip_atomic_fetch_add((unsigned*)(ws + WS_CTL) + CW_QUEUE, 1u, __ATOMIC_RELAXED, __HIP_MEMORY_SCOPE_AGENT);
;                         __syncthreads(); const unsigned idx = *qslot; __syncthreads();
;                         if (idx >= 2048u + 256u) break;
;                         if (idx >= 256u) { const unsigned iu = idx - 256u; const int qb = 31 - (int)(iu >> 6), bh = (int)(iu & 63u);
;                             const float kmx = sqrtf(__uint_as_float(__hip_atomic_load(kmax2 + bh, __ATOMIC_RELAXED, __HIP_MEMORY_SCOPE_AGENT))) * 1.01f;
;     ...
;                             attn_body::attn_unit<0, 8>(bh >> 4, bh & 15, qb, Qb, Kb, Vb, (attn_body::bf16*)(ws + WS_OB), (char*)lds + RING_OFF, cs2 + (size_t)bh * 8192, nullptr, kmx);
;     ...
;                         } else { const int u = (int)idx;
;     ...
;                             sample_unit<1>(u >> 4, u & 15, lds3 + RING_OFF, A);
.LBB0_198:
	s_and_saveexec_b64 s[42:43], s[40:41]
	s_cbranch_execz .LBB0_202
	s_mov_b64 s[46:47], exec
	v_mbcnt_lo_u32_b32 v0, s46, 0
	v_mbcnt_hi_u32_b32 v0, s47, v0
	v_cmp_eq_u32_e32 vcc, 0, v0
	s_and_saveexec_b64 s[44:45], vcc
	s_cbranch_execz .LBB0_201
	v_readlane_b32 s4, v255, 52
	v_readlane_b32 s5, v255, 53
	s_waitcnt vmcnt(0)
	v_mov_b32_e32 v1, v248
	s_nop 2
	global_atomic_add v248, v3, v216, s[4:5] sc0
.LBB0_201:
	s_or_b64 exec, exec, s[44:45]
	v_readfirstlane_b32 s2, v1
	s_nop 1
	v_add_u32_e32 v0, s2, v0
	v_readlane_b32 s2, v255, 19
	s_nop 1
	v_mov_b32_e32 v1, s2
	ds_write_b32 v1, v0
.LBB0_202:
	s_or_b64 exec, exec, s[42:43]
	v_readlane_b32 s2, v255, 19
	s_waitcnt lgkmcnt(0)
	s_barrier
	v_mov_b32_e32 v0, s2
	ds_read_b32 v0, v0
	s_movk_i32 s2, 0x8ff
	s_mov_b64 s[42:43], -1
	s_waitcnt lgkmcnt(0)
	s_barrier
	v_cmp_lt_u32_e32 vcc, s2, v0
	v_readfirstlane_b32 s5, v0
	s_cbranch_vccnz .LBB0_197
	s_cmpk_lt_u32 s5, 0x100
	s_cbranch_scc0 .LBB0_246
	v_mov_b32_e32 v1, v212
	s_and_b32 s19, s5, 0xf0
	s_or_b32 s4, s19, 0x8000
	v_ashrrev_i32_e32 v6, 5, v1
	v_add_u32_e32 v4, s4, v6
	v_ashrrev_i32_e32 v5, 31, v4
	s_and_b32 s28, s5, 15
	v_lshlrev_b32_e32 v0, 1, v1
	v_lshlrev_b64 v[4:5], 11, v[4:5]
	v_and_b32_e32 v0, 62, v0
	v_lshl_add_u64 v[4:5], s[92:93], 0, v[4:5]
	s_lshl_b32 s6, s28, 7
	s_mov_b32 s7, s29
	v_lshl_add_u64 v[4:5], v[4:5], 0, s[6:7]
	v_lshlrev_b32_e32 v2, 1, v0
	v_lshl_add_u64 v[4:5], v[4:5], 0, v[2:3]
	global_load_dword v2, v[4:5], off
	s_load_dwordx4 s[56:59], s[0:1], 0x20
	s_load_dwordx2 s[26:27], s[0:1], 0x30
	v_readlane_b32 s66, v255, 57
	v_readlane_b32 s67, v255, 58
	s_lshr_b32 s42, s5, 4
	s_lshl_b32 s44, s28, 2
	s_lshl_b32 s43, s42, 16
	s_add_i32 s43, s43, s44
	s_lshl_b32 s42, s42, 10
	s_add_i32 s42, s42, s44
	v_lshl_add_u32 v60, v1, 6, s43
	v_add_u32_e32 v61, 0x8000, v60
	v_lshl_add_u32 v62, v1, 6, s42
	v_cmp_gt_u32_e32 vcc, 16, v1
	s_waitcnt lgkmcnt(0)
	global_load_dword v63, v60, s[26:27]
	global_load_dword v64, v61, s[26:27]
	s_and_saveexec_b64 s[64:65], vcc
	global_load_dword v65, v62, s[66:67]
	s_mov_b64 exec, s[64:65]
	v_lshlrev_b32_e32 v4, 8, v6
	v_lshlrev_b32_e32 v0, 2, v0
	v_add3_u32 v0, 0, v4, v0
	v_cmp_lt_u32_e32 vcc, 63, v1
	s_waitcnt vmcnt(0)
	v_lshlrev_b32_e32 v4, 16, v2
	v_and_b32_e32 v5, 0xffff0000, v2
	ds_write_b64 v0, v[4:5]
	v_lshlrev_b32_e32 v60, 2, v1
	v_cmp_gt_u32_e64 s[64:65], 16, v1
	ds_write_b32 v60, v63 offset:4096
	ds_write_b32 v60, v64 offset:6144
	s_nop 1
	s_and_saveexec_b64 s[66:67], s[64:65]
	ds_write_b32 v60, v65 offset:8192
	s_mov_b64 exec, s[66:67]
	s_waitcnt lgkmcnt(0)
	s_barrier
	s_and_saveexec_b64 s[6:7], vcc
	s_xor_b64 s[42:43], exec, s[6:7]
	s_or_saveexec_b64 s[60:61], s[42:43]
	s_lshr_b32 s2, s5, 4
	v_and_b32_e32 v0, 63, v1
	v_mov_b64_e32 v[4:5], s[28:29]
	s_xor_b64 exec, exec, s[60:61]
	s_cbranch_execz .LBB0_216
	v_and_b32_e32 v2, 64, v219
	v_subrev_u32_e32 v10, 32, v219
	v_add_u32_e32 v5, -1, v219
	v_add_u32_e32 v6, -2, v219
	v_add_u32_e32 v7, -4, v219
	v_add_u32_e32 v8, -8, v219
	v_add_u32_e32 v9, -16, v219
	v_cmp_lt_i32_e64 s[50:51], v10, v2
	s_lshl_b32 s7, s28, 2
	v_readlane_b32 s22, v255, 57
	v_cmp_lt_i32_e32 vcc, v5, v2
	v_cmp_lt_i32_e64 s[42:43], v6, v2
	v_cmp_lt_i32_e64 s[44:45], v7, v2
	v_cmp_lt_i32_e64 s[46:47], v8, v2
	v_cmp_lt_i32_e64 s[48:49], v9, v2
	v_cndmask_b32_e64 v2, v10, v219, s[50:51]
	s_add_u32 s62, s22, s7
	v_readlane_b32 s7, v255, 58
	v_lshlrev_b32_e32 v10, 2, v2
	v_lshlrev_b32_e32 v2, 4, v1
	v_bfrev_b32_e32 v4, 0.5
	s_addc_u32 s63, s7, 0
	v_cndmask_b32_e32 v5, v5, v219, vcc
	v_cndmask_b32_e64 v6, v6, v219, s[42:43]
	v_cndmask_b32_e64 v7, v7, v219, s[44:45]
	v_cndmask_b32_e64 v8, v8, v219, s[46:47]
	v_cndmask_b32_e64 v9, v9, v219, s[48:49]
	s_add_i32 s7, 0, 0x1000
	v_lshl_add_u32 v2, s2, 14, v2
	s_mov_b32 s6, 0
	v_lshl_or_b32 v4, v219, 2, v4
	v_lshlrev_b32_e32 v5, 2, v5
	v_cmp_eq_u32_e32 vcc, 0, v0
	v_lshlrev_b32_e32 v6, 2, v6
	v_cmp_gt_u32_e64 s[42:43], 2, v0
	v_lshlrev_b32_e32 v7, 2, v7
	v_cmp_gt_u32_e64 s[44:45], 4, v0
	v_lshlrev_b32_e32 v8, 2, v8
	v_cmp_gt_u32_e64 s[46:47], 8, v0
	v_lshlrev_b32_e32 v9, 2, v9
	v_cmp_gt_u32_e64 s[48:49], 16, v0
	v_cmp_gt_u32_e64 s[50:51], 32, v0
	v_lshl_add_u32 v11, v1, 2, s7
	s_or_b32 s7, s19, 0xfffffc00
	v_or_b32_e32 v2, s28, v2
	v_mov_b32_e32 v13, 0
	v_mov_b32_e32 v12, v1
	s_branch .LBB0_207

; template <int FOX> __device__ __forceinline__ void sample_unit(int s, int h, LAS unsigned char* lds, const KA& A) {
;     ...
;         for (int c = 0; c < 17; ++c) { const int j = c * 64 + lane;
;             float v = (j < 1024) ? clf[(size_t)(s * 1024 + j) * 16 + h] : ((j < 1040) ? nlf[(size_t)(s * 16 + j - 1024) * 16 + h] : 0.f);
; #pragma unroll
;             for (int d = 1; d < 64; d <<= 1) { const float t = __shfl_up(v, d); if (lane >= d) v += t; }
;             v += carry; if (j < 1040) cum[j] = v; carry = __shfl(v, 63); } }
.LBB0_207:
	v_add_u32_e32 v15, s6, v11
	ds_read_b32 v14, v15
	v_cmp_gt_u32_e64 s[54:55], s69, v12
	s_waitcnt lgkmcnt(0)
	s_nop 1
	v_cndmask_b32_e64 v14, 0, v14, s[54:55]
	ds_bpermute_b32 v15, v5, v14
	v_cmp_gt_i32_e64 s[54:55], s69, v12
	s_waitcnt lgkmcnt(0)
	v_add_f32_e32 v15, v14, v15
	v_cndmask_b32_e32 v14, v15, v14, vcc
	ds_bpermute_b32 v15, v6, v14
	s_waitcnt lgkmcnt(0)
	v_add_f32_e32 v15, v14, v15
	v_cndmask_b32_e64 v14, v15, v14, s[42:43]
	ds_bpermute_b32 v15, v7, v14
	s_waitcnt lgkmcnt(0)
	v_add_f32_e32 v15, v14, v15
	v_cndmask_b32_e64 v14, v15, v14, s[44:45]
	ds_bpermute_b32 v15, v8, v14
	s_waitcnt lgkmcnt(0)
	v_add_f32_e32 v15, v14, v15
	v_cndmask_b32_e64 v14, v15, v14, s[46:47]
	ds_bpermute_b32 v15, v9, v14
	s_waitcnt lgkmcnt(0)
	v_add_f32_e32 v15, v14, v15
	v_cndmask_b32_e64 v14, v15, v14, s[48:49]
	ds_bpermute_b32 v15, v10, v14
	s_waitcnt lgkmcnt(0)
	v_add_f32_e32 v15, v14, v15
	v_cndmask_b32_e64 v14, v15, v14, s[50:51]
	v_add_f32_e32 v13, v13, v14
	s_and_saveexec_b64 s[64:65], s[54:55]
	s_cbranch_execz .LBB0_206
	v_add_u32_e32 v14, s6, v11
	ds_write_b32 v14, v13
	s_branch .LBB0_206

;     __host__ __device__ bool next(int i, Unit& u) const {
;         const long L = (long)i * G + c; if (L >= nwg) return false;
;         int wgid = (int)L; { const int q = nwg / NXCD, r = nwg % NXCD, xcd = wgid % NXCD, off = wgid / NXCD; wgid = (xcd < r ? xcd * (q + 1) : r * (q + 1) + (xcd - r) * q) + off; }
;         const int nig = WGM * nN, gid = wgid / nig, fm = gid * WGM, gsz = (nM - fm) < WGM ? (nM - fm) : WGM;
;         u.pm = fm + ((wgid % nig) % gsz); u.pn = (wgid % nig) / gsz; return true;
.LBB0_640:
	s_ashr_i32 s26, s26, 3
	s_add_i32 s26, s44, s26
	s_ashr_i32 s33, s26, 31
	s_lshr_b32 s33, s33, 24
	s_add_i32 s33, s26, s33
	s_ashr_i32 s42, s33, 8
	s_lshl_b32 s43, s42, 3
	s_and_b32 s33, s33, 0xffffff00
	s_sub_i32 s26, s26, s33
	s_lshr_b32 s42, s26, 3
	s_and_b32 s26, s26, 7
	s_add_i32 s44, s43, s26
